# attention tile loop: o accumulators kept in home registers (PV MFMAs read/write home directly, rescale in place), 48 v_mov_b64 per tile removed; copies only in the once-per-item meta path and at loop
# speedup vs baseline: 1.0289x; 1.0103x over previous
; __device__ __forceinline__ void attn_item(const AttnItem it, unsigned char* smem) {
;     ...
;   for (int ti = 0; ti < nt_all; ++ti) {
;     unsigned char* sK = smem + (ti & 1) * 20480; unsigned char* sV = sK + 12288;
;     if (ti + 1 < nt_all) {
.LBB0_1550:


; __device__ __forceinline__ void attn_item(const AttnItem it, unsigned char* smem) {
;     ...
;     if (ti + 1 < nt_all) {
;       const long koff = 16 + 64 * (long)ti;
;       rk[0] = *(const u32x4*)(kptr[0] + koff * 768);
;       rk[1] = *(const u32x4*)(kptr[1] + koff * 768);
;       rv = *(const u32x4*)(vptr + koff);
;     }
	v_mov_b32_e32 v198, v3
	v_mov_b32_e32 v197, v199
	v_mov_b64_e32 v[146:147], v[0:1]
	s_cmp_lt_u32 s11, s15
	s_cselect_b64 s[6:7], -1, 0
	s_cmp_ge_u32 s11, s15
	s_cbranch_scc1 .LBB0_1552

; __device__ __forceinline__ void attn_item(const AttnItem it, unsigned char* smem) {
;     ...
;     if (ti == 0) tile_body(std::true_type{}, sK, sV);
;     else if (ti <= my_tiles) tile_body(std::false_type{}, sK, sV);
.LBB0_1552:
	s_bitcmp1_b32 s11, 0
	s_cselect_b32 s12, 0x5000, 0
	s_cmp_lg_u32 s11, 0
	s_cbranch_scc0 .LBB0_1561


; __device__ __forceinline__ void attn_item(const AttnItem it, unsigned char* smem) {
;     ...
;     if (ti == 0) tile_body(std::true_type{}, sK, sV);
;     else if (ti <= my_tiles) tile_body(std::false_type{}, sK, sV);
	v_cmp_le_i32_e32 vcc, s11, v169
	v_mov_b64_e32 v[0:1], v[146:147]
	v_mov_b32_e32 v3, v198
	v_mov_b32_e32 v199, v197


; DI f32x4 mfma16(bf16x8 a, bf16x8 b, f32x4 c) { return __builtin_amdgcn_mfma_f32_16x16x32_bf16(a, b, c, 0, 0, 0); }
; __device__ __forceinline__ void attn_item(const AttnItem it, unsigned char* smem) {
;     ...
;     for (int kf = 0; kf < NKF; ++kf) {
; #pragma unroll
;       for (int ks = 0; ks < 3; ++ks) {
;         bf16x8 kfr = *(const bf16x8*)(sK + ((kf * 3 + ks) << 10) + swz(r, q));
; #pragma unroll
;         for (int f = 0; f < 2; ++f) s[kf][f] = mfma16(kfr, qf[f][ks], s[kf][f]);
;     ...
;     if (ti == 0) tile_body(std::true_type{}, sK, sV);
;     else if (ti <= my_tiles) tile_body(std::false_type{}, sK, sV);
	s_and_saveexec_b64 s[8:9], vcc
	s_cbranch_execz .LBB0_1557
	v_add3_u32 v0, s12, v194, v171
	ds_read_b128 v[72:75], v0
	ds_read_b128 v[76:79], v0 offset:1024
	v_cmp_lt_i32_e32 vcc, v175, v176


; DI f32x4 mfma16(bf16x8 a, bf16x8 b, f32x4 c) { return __builtin_amdgcn_mfma_f32_16x16x32_bf16(a, b, c, 0, 0, 0); }
; __device__ __forceinline__ void attn_item(const AttnItem it, unsigned char* smem) {
;     ...
;     for (int kf = 0; kf < NKF; ++kf) {
; #pragma unroll
;       for (int ks = 0; ks < 3; ++ks) {
;         bf16x8 kfr = *(const bf16x8*)(sK + ((kf * 3 + ks) << 10) + swz(r, q));
; #pragma unroll
;         for (int f = 0; f < 2; ++f) s[kf][f] = mfma16(kfr, qf[f][ks], s[kf][f]);
	s_waitcnt lgkmcnt(1)
	v_mfma_f32_16x16x32_bf16 v[80:83], v[72:75], v[4:7], 0


; DI f32x4 mfma16(bf16x8 a, bf16x8 b, f32x4 c) { return __builtin_amdgcn_mfma_f32_16x16x32_bf16(a, b, c, 0, 0, 0); }
; __device__ __forceinline__ void attn_item(const AttnItem it, unsigned char* smem) {
;     ...
;     for (int kf = 0; kf < NKF; ++kf) {
; #pragma unroll
;       for (int ks = 0; ks < 3; ++ks) {
;         bf16x8 kfr = *(const bf16x8*)(sK + ((kf * 3 + ks) << 10) + swz(r, q));
; #pragma unroll
;         for (int f = 0; f < 2; ++f) s[kf][f] = mfma16(kfr, qf[f][ks], s[kf][f]);
	v_mfma_f32_16x16x32_bf16 v[72:75], v[72:75], v[16:19], 0

; DI f32x4 mfma16(bf16x8 a, bf16x8 b, f32x4 c) { return __builtin_amdgcn_mfma_f32_16x16x32_bf16(a, b, c, 0, 0, 0); }
; __device__ __forceinline__ void attn_item(const AttnItem it, unsigned char* smem) {
;     ...
;     for (int kf = 0; kf < NKF; ++kf) {
; #pragma unroll
;       for (int ks = 0; ks < 3; ++ks) {
;         bf16x8 kfr = *(const bf16x8*)(sK + ((kf * 3 + ks) << 10) + swz(r, q));
; #pragma unroll
;         for (int f = 0; f < 2; ++f) s[kf][f] = mfma16(kfr, qf[f][ks], s[kf][f]);
;       }
;     }
;     float mx[2];
; #pragma unroll
;     for (int f = 0; f < 2; ++f) {
;       float m_ = s[0][f][0];
; #pragma unroll
;       for (int kf = 0; kf < NKF; ++kf)
; #pragma unroll
;         for (int j = 0; j < 4; ++j) m_ = fmaxf(m_, s[kf][f][j]);
;       m_ = fmaxf(m_, __shfl_xor(m_, 16));
;       m_ = fmaxf(m_, __shfl_xor(m_, 32));
;       mx[f] = m_;
;     }
	v_mov_b32_e32 v199, v197
	s_waitcnt lgkmcnt(0)
	v_mfma_f32_16x16x32_bf16 v[80:83], v[76:79], v[8:11], v[80:83]
	v_mfma_f32_16x16x32_bf16 v[72:75], v[76:79], v[20:23], v[72:75]
	ds_read_b128 v[76:79], v0 offset:2048
	ds_read_b128 v[84:87], v0 offset:3072
	s_waitcnt lgkmcnt(1)
	v_mfma_f32_16x16x32_bf16 v[92:95], v[76:79], v[12:15], v[80:83]
	v_mfma_f32_16x16x32_bf16 v[124:127], v[76:79], v[24:27], v[72:75]
	s_nop 6
	v_max_f32_e32 v3, v93, v93
	s_waitcnt lgkmcnt(0)
	v_mfma_f32_16x16x32_bf16 v[72:75], v[84:87], v[4:7], 0
	v_mfma_f32_16x16x32_bf16 v[76:79], v[84:87], v[16:19], 0
	ds_read_b128 v[80:83], v0 offset:4096
	ds_read_b128 v[84:87], v0 offset:5120
	s_waitcnt lgkmcnt(1)
	v_mfma_f32_16x16x32_bf16 v[72:75], v[80:83], v[8:11], v[72:75]
	v_mfma_f32_16x16x32_bf16 v[76:79], v[80:83], v[20:23], v[76:79]
	s_waitcnt lgkmcnt(0)
	v_mfma_f32_16x16x32_bf16 v[120:123], v[84:87], v[12:15], v[72:75]
	v_mfma_f32_16x16x32_bf16 v[116:119], v[84:87], v[24:27], v[76:79]
	s_nop 3
	ds_read_b128 v[72:75], v0 offset:6144
	ds_read_b128 v[76:79], v0 offset:7168
	ds_read_b128 v[84:87], v0 offset:8192
	ds_read_b128 v[88:91], v0 offset:9216
	ds_read_b128 v[96:99], v0 offset:10240
	ds_read_b128 v[100:103], v0 offset:11264
	s_waitcnt lgkmcnt(5)
	v_mfma_f32_16x16x32_bf16 v[80:83], v[72:75], v[4:7], 0
	v_cndmask_b32_e32 v0, v174, v175, vcc
	v_lshlrev_b32_e32 v0, 2, v0
	v_cmp_lt_i32_e32 vcc, v177, v176
	v_mfma_f32_16x16x32_bf16 v[72:75], v[72:75], v[16:19], 0
	s_nop 0
	v_cndmask_b32_e32 v1, v174, v177, vcc
	v_lshlrev_b32_e32 v1, 2, v1
	s_waitcnt lgkmcnt(4)
	v_mfma_f32_16x16x32_bf16 v[80:83], v[76:79], v[8:11], v[80:83]
	v_mfma_f32_16x16x32_bf16 v[72:75], v[76:79], v[20:23], v[72:75]
	s_waitcnt lgkmcnt(2)
	v_mfma_f32_16x16x32_bf16 v[76:79], v[88:91], v[4:7], 0
	s_waitcnt lgkmcnt(1)
	v_mfma_f32_16x16x32_bf16 v[76:79], v[96:99], v[8:11], v[76:79]
	s_waitcnt lgkmcnt(0)
	v_mfma_f32_16x16x32_bf16 v[132:135], v[100:103], v[12:15], v[76:79]
	v_mfma_f32_16x16x32_bf16 v[76:79], v[84:87], v[24:27], v[72:75]
	v_mfma_f32_16x16x32_bf16 v[72:75], v[88:91], v[16:19], 0


; DI f32x4 mfma16(bf16x8 a, bf16x8 b, f32x4 c) { return __builtin_amdgcn_mfma_f32_16x16x32_bf16(a, b, c, 0, 0, 0); }
; __device__ __forceinline__ void attn_item(const AttnItem it, unsigned char* smem) {
;     ...
;     for (int kf = 0; kf < NKF; ++kf) {
; #pragma unroll
;       for (int ks = 0; ks < 3; ++ks) {
;         bf16x8 kfr = *(const bf16x8*)(sK + ((kf * 3 + ks) << 10) + swz(r, q));
; #pragma unroll
;         for (int f = 0; f < 2; ++f) s[kf][f] = mfma16(kfr, qf[f][ks], s[kf][f]);
;       }
;     }
	v_mfma_f32_16x16x32_bf16 v[72:75], v[96:99], v[20:23], v[72:75]


; DI f32x4 mfma16(bf16x8 a, bf16x8 b, f32x4 c) { return __builtin_amdgcn_mfma_f32_16x16x32_bf16(a, b, c, 0, 0, 0); }
; __device__ __forceinline__ void attn_item(const AttnItem it, unsigned char* smem) {
;     ...
;     for (int kf = 0; kf < NKF; ++kf) {
; #pragma unroll
;       for (int ks = 0; ks < 3; ++ks) {
;         bf16x8 kfr = *(const bf16x8*)(sK + ((kf * 3 + ks) << 10) + swz(r, q));
; #pragma unroll
;         for (int f = 0; f < 2; ++f) s[kf][f] = mfma16(kfr, qf[f][ks], s[kf][f]);
;       }
;     }
	v_mfma_f32_16x16x32_bf16 v[128:131], v[84:87], v[12:15], v[80:83]


; __device__ __forceinline__ void attn_item(const AttnItem it, unsigned char* smem) {
;     ...
;     float mx[2];
; #pragma unroll
;     for (int f = 0; f < 2; ++f) {
;       float m_ = s[0][f][0];
; #pragma unroll
;       for (int kf = 0; kf < NKF; ++kf)
; #pragma unroll
;         for (int j = 0; j < 4; ++j) m_ = fmaxf(m_, s[kf][f][j]);
;       m_ = fmaxf(m_, __shfl_xor(m_, 16));
;       m_ = fmaxf(m_, __shfl_xor(m_, 32));
;       mx[f] = m_;
;     }
	s_nop 0
	v_max_f32_e32 v80, v92, v92
	v_max_f32_e32 v81, v125, v125
	v_max_f32_e32 v82, v124, v124
	v_max_f32_e32 v3, v80, v3
	v_max_f32_e32 v81, v82, v81
	v_max3_f32 v3, v3, v94, v95
	v_max3_f32 v81, v81, v126, v127
	v_max3_f32 v3, v3, v120, v121
	v_max3_f32 v81, v81, v116, v117
	v_mfma_f32_16x16x32_bf16 v[72:75], v[100:103], v[24:27], v[72:75]
	v_max3_f32 v3, v3, v122, v123
	v_max3_f32 v81, v81, v118, v119
	v_max3_f32 v3, v3, v128, v129
	v_max3_f32 v81, v81, v76, v77
	v_max3_f32 v3, v3, v130, v131
	v_max3_f32 v81, v81, v78, v79
	v_max3_f32 v3, v3, v132, v133
	s_nop 0
	v_max3_f32 v81, v81, v72, v73
	v_max3_f32 v3, v3, v134, v135
	v_max3_f32 v81, v81, v74, v75
	ds_bpermute_b32 v80, v0, v3
	ds_bpermute_b32 v0, v0, v81


; __device__ __forceinline__ void attn_item(const AttnItem it, unsigned char* smem) {
;     ...
;       m_ = fmaxf(m_, __shfl_xor(m_, 16));
;       m_ = fmaxf(m_, __shfl_xor(m_, 32));
;       mx[f] = m_;
;     }
;     const bool need = (mx[0] > mrun[0] + 8.f) || (mx[1] > mrun[1] + 8.f);
;     if (__builtin_amdgcn_ballot_w64(need) != 0ull) {
	s_waitcnt lgkmcnt(1)
	v_max_f32_e32 v80, v80, v80
	s_waitcnt lgkmcnt(0)
	v_max_f32_e32 v0, v0, v0
	v_max_f32_e32 v3, v3, v80
	v_max_f32_e32 v0, v81, v0
	ds_bpermute_b32 v80, v1, v3
	ds_bpermute_b32 v1, v1, v0
	s_waitcnt lgkmcnt(1)
	v_max_f32_e32 v80, v80, v80
	s_waitcnt lgkmcnt(0)
	v_max_f32_e32 v1, v1, v1
	v_max_f32_e32 v149, v3, v80
	v_max_f32_e32 v148, v0, v1
	v_add_f32_e32 v0, 0x41000000, v198
	v_cmp_gt_f32_e32 vcc, v149, v0
	v_add_f32_e32 v0, 0x41000000, v197
	v_cmp_gt_f32_e64 s[0:1], v148, v0

; __device__ __forceinline__ void attn_item(const AttnItem it, unsigned char* smem) {
;     ...
;     const bool need = (mx[0] > mrun[0] + 8.f) || (mx[1] > mrun[1] + 8.f);
;     if (__builtin_amdgcn_ballot_w64(need) != 0ull) {
	s_or_b64 vcc, vcc, s[0:1]

; DI f32x4 mfma16(bf16x8 a, bf16x8 b, f32x4 c) { return __builtin_amdgcn_mfma_f32_16x16x32_bf16(a, b, c, 0, 0, 0); }
; __device__ __forceinline__ void attn_item(const AttnItem it, unsigned char* smem) {
;     ...
;     if (__builtin_amdgcn_ballot_w64(need) != 0ull) {
; #pragma unroll
;       for (int f = 0; f < 2; ++f) {
;         const float mnew = fmaxf(mrun[f], mx[f]);
;         const float alpha = __builtin_amdgcn_exp2f(mrun[f] - mnew);
;         mrun[f] = mnew;
;         lrun[f] *= alpha;
; #pragma unroll
;         for (int d = 0; d < 4; ++d)
; #pragma unroll
;           for (int j = 0; j < 4; ++j) o[d][f][j] *= alpha;
;       }
;     }
;     bf16x8 pf[2][NKS];
; #pragma unroll
;     for (int f = 0; f < 2; ++f) {
;       float pv[NKF][4];
;       float ps = 0.f;
; #pragma unroll
;       for (int kf = 0; kf < NKF; ++kf)
; #pragma unroll
;         for (int j = 0; j < 4; ++j) { pv[kf][j] = __builtin_amdgcn_exp2f(s[kf][f][j] - mrun[f]); ps += pv[kf][j]; }
;       lrun[f] += ps;
;       if constexpr (META) {
;         u32x4 w = {pack2(pv[0][0], pv[0][1]), pack2(pv[0][2], pv[0][3]), 0u, 0u};
;         pf[f][0] = __builtin_bit_cast(bf16x8, w);
;       } else {
; #pragma unroll
;         for (int ks = 0; ks < 2; ++ks) {
;           u32x4 w = {pack2(pv[2 * ks][0], pv[2 * ks][1]), pack2(pv[2 * ks][2], pv[2 * ks][3]),
;                      pack2(pv[2 * ks + 1][0], pv[2 * ks + 1][1]), pack2(pv[2 * ks + 1][2], pv[2 * ks + 1][3])};
;           pf[f][ks] = __builtin_bit_cast(bf16x8, w);
;         }
;       }
;     }
; #pragma unroll
;     for (int ks = 0; ks < NKS; ++ks) {
; #pragma unroll
;       for (int d = 0; d < 4; ++d) {
;         const unsigned char* vb = sV + ((d * 2 + ks) << 10) + r * 64;
;         const int x = (r >> 2) << 1;
;         u32x2 lo = *(const u32x2*)(vb + (((q) ^ x) << 3));
;         u32x2 hi = *(const u32x2*)(vb + (((4 + q) ^ x) << 3));
;         u32x4 w = {lo[0], lo[1], hi[0], hi[1]};
;         bf16x8 vf = __builtin_bit_cast(bf16x8, w);
; #pragma unroll
;         for (int f = 0; f < 2; ++f) o[d][f] = mfma16(vf, pf[f][ks], o[d][f]);
;       }
;     }
	v_mov_b32_e32 v3, v198
	v_mov_b64_e32 v[0:1], v[146:147]
	s_cbranch_vccz .LBB0_1556
	v_max_f32_e32 v0, v149, v149
	v_max_f32_e32 v1, v198, v198
	v_max_f32_e32 v3, v1, v0
	v_sub_f32_e32 v0, v198, v3
	v_exp_f32_e32 v0, v0
	v_max_f32_e32 v80, v197, v197
	v_pk_mul_f32 v[70:71], v[70:71], v[0:1] op_sel_hi:[1,0]
	v_pk_mul_f32 v[68:69], v[68:69], v[0:1] op_sel_hi:[1,0]
	v_pk_mul_f32 v[62:63], v[62:63], v[0:1] op_sel_hi:[1,0]
	v_pk_mul_f32 v[60:61], v[60:61], v[0:1] op_sel_hi:[1,0]
	v_pk_mul_f32 v[54:55], v[54:55], v[0:1] op_sel_hi:[1,0]
	v_pk_mul_f32 v[52:53], v[52:53], v[0:1] op_sel_hi:[1,0]
	v_max_f32_e32 v1, v148, v148
	v_max_f32_e32 v199, v80, v1
	v_sub_f32_e32 v1, v197, v199
	v_exp_f32_e32 v88, v1
	v_mov_b32_e32 v89, v0
	v_pk_mul_f32 v[46:47], v[46:47], v[0:1] op_sel_hi:[1,0]
	v_pk_mul_f32 v[44:45], v[44:45], v[0:1] op_sel_hi:[1,0]
	v_pk_mul_f32 v[0:1], v[146:147], v[88:89]
	v_pk_mul_f32 v[66:67], v[66:67], v[88:89] op_sel_hi:[1,0]
	v_pk_mul_f32 v[64:65], v[64:65], v[88:89] op_sel_hi:[1,0]
	v_pk_mul_f32 v[58:59], v[58:59], v[88:89] op_sel_hi:[1,0]
	v_pk_mul_f32 v[56:57], v[56:57], v[88:89] op_sel_hi:[1,0]
	v_pk_mul_f32 v[50:51], v[50:51], v[88:89] op_sel_hi:[1,0]
	v_pk_mul_f32 v[48:49], v[48:49], v[88:89] op_sel_hi:[1,0]
	v_pk_mul_f32 v[42:43], v[42:43], v[88:89] op_sel_hi:[1,0]
	v_pk_mul_f32 v[40:41], v[40:41], v[88:89] op_sel_hi:[1,0]
.LBB0_1556:
	v_sub_f32_e32 v124, v124, v199
	v_sub_f32_e32 v92, v92, v3
	v_exp_f32_e32 v204, v124
	v_sub_f32_e32 v124, v125, v199
	v_sub_f32_e32 v118, v118, v199
	v_sub_f32_e32 v76, v76, v199
	v_exp_f32_e32 v205, v92
	v_sub_f32_e32 v92, v93, v3
	v_exp_f32_e32 v206, v124
	v_sub_f32_e32 v124, v126, v199
	v_exp_f32_e32 v160, v118
	v_sub_f32_e32 v118, v119, v199
	v_exp_f32_e32 v156, v76
	v_sub_f32_e32 v76, v77, v199
	v_add_u32_e32 v77, s12, v171
	v_exp_f32_e32 v207, v92
	v_sub_f32_e32 v92, v94, v3
	v_exp_f32_e32 v208, v124
	v_sub_f32_e32 v124, v127, v199
	v_exp_f32_e32 v154, v118
	v_add_u32_e32 v118, v77, v195
	v_add_u32_e32 v119, v77, v196
	v_exp_f32_e32 v209, v92
	v_sub_f32_e32 v92, v95, v3
	v_exp_f32_e32 v162, v124
	ds_read2st64_b64 v[124:127], v118 offset0:24 offset1:26
	ds_read2st64_b64 v[200:203], v119 offset0:24 offset1:26
	ds_read2st64_b64 v[212:215], v118 offset0:28 offset1:30
	ds_read2st64_b64 v[216:219], v119 offset0:28 offset1:30
	v_exp_f32_e32 v163, v92
	v_sub_f32_e32 v92, v120, v3
	v_sub_f32_e32 v116, v116, v199
	v_exp_f32_e32 v165, v92
	v_sub_f32_e32 v92, v121, v3
	v_exp_f32_e32 v164, v116
	v_sub_f32_e32 v116, v117, v199
	v_exp_f32_e32 v167, v92
	v_sub_f32_e32 v92, v122, v3
	v_exp_f32_e32 v166, v116
	v_pk_add_f32 v[116:117], v[204:205], 0 op_sel_hi:[1,0]
	v_exp_f32_e32 v161, v92
	v_sub_f32_e32 v92, v123, v3
	v_pk_add_f32 v[116:117], v[206:207], v[116:117]
	v_exp_f32_e32 v155, v92
	v_cvt_pk_bf16_f32 v120, v205, v207
	v_cvt_pk_bf16_f32 v121, v209, v163
	v_pk_add_f32 v[116:117], v[208:209], v[116:117]
	v_cvt_pk_bf16_f32 v205, v208, v162
	s_waitcnt lgkmcnt(3)
	v_mov_b32_e32 v208, v124
	v_mov_b32_e32 v209, v125
	s_waitcnt lgkmcnt(2)
	v_mov_b32_e32 v210, v200
	v_mov_b32_e32 v211, v201
	s_waitcnt lgkmcnt(1)
	v_mov_b32_e32 v220, v212
	v_mov_b32_e32 v221, v213
	s_waitcnt lgkmcnt(0)
	v_mov_b32_e32 v222, v216
	v_mov_b32_e32 v223, v217
	v_exp_f32_e32 v158, v76
	v_sub_f32_e32 v76, v78, v199
	v_cvt_pk_bf16_f32 v122, v165, v167
	v_cvt_pk_bf16_f32 v123, v161, v155
	v_cvt_pk_bf16_f32 v204, v204, v206
	v_cvt_pk_bf16_f32 v206, v164, v166
	v_cvt_pk_bf16_f32 v207, v160, v154
	v_exp_f32_e32 v152, v76
	v_sub_f32_e32 v76, v79, v199
	v_mfma_f32_16x16x32_bf16 v[104:107], v[208:211], v[120:123], v[68:71]
	v_exp_f32_e32 v148, v76
	ds_read2st64_b64 v[224:227], v118 offset0:36 offset1:38
	ds_read2st64_b64 v[228:231], v119 offset0:36 offset1:38
	v_mfma_f32_16x16x32_bf16 v[112:115], v[208:211], v[204:207], v[64:67]
	ds_read2st64_b64 v[208:211], v119 offset0:32 offset1:34
	v_sub_f32_e32 v92, v128, v3
	v_exp_f32_e32 v157, v92
	v_mfma_f32_16x16x32_bf16 v[76:79], v[220:223], v[120:123], v[60:63]
	v_sub_f32_e32 v92, v129, v3
	v_exp_f32_e32 v159, v92
	v_sub_f32_e32 v92, v130, v3
	ds_read2st64_b64 v[96:99], v118 offset0:32 offset1:34
	v_mfma_f32_16x16x32_bf16 v[108:111], v[220:223], v[204:207], v[56:59]
	s_waitcnt lgkmcnt(1)
	v_mov_b32_e32 v222, v208
	v_mov_b32_e32 v223, v209
	v_mov_b32_e32 v232, v224
	s_waitcnt lgkmcnt(0)
	v_mov_b32_e32 v220, v96
	v_mov_b32_e32 v221, v97
	v_mov_b32_e32 v233, v225
	v_mov_b32_e32 v234, v228
	v_mov_b32_e32 v235, v229
	v_exp_f32_e32 v153, v92
	v_sub_f32_e32 v92, v131, v3
	v_exp_f32_e32 v149, v92
	v_sub_f32_e32 v92, v132, v3
	v_exp_f32_e32 v151, v92
	v_sub_f32_e32 v92, v133, v3
	v_exp_f32_e32 v133, v92
	v_sub_f32_e32 v92, v134, v3
	v_sub_f32_e32 v72, v72, v199
	v_exp_f32_e32 v129, v92
	v_sub_f32_e32 v92, v135, v3
	v_exp_f32_e32 v150, v72
	v_sub_f32_e32 v72, v73, v199
	v_mfma_f32_16x16x32_bf16 v[84:87], v[220:223], v[120:123], v[52:55]
	v_exp_f32_e32 v131, v92
	v_exp_f32_e32 v132, v72
	v_sub_f32_e32 v72, v74, v199
	v_mfma_f32_16x16x32_bf16 v[118:121], v[232:235], v[120:123], v[44:47]
	v_mov_b32_e32 v200, v126
	v_mov_b32_e32 v201, v127
	v_exp_f32_e32 v128, v72
	v_mfma_f32_16x16x32_bf16 v[122:125], v[232:235], v[204:207], v[40:43]
	v_sub_f32_e32 v72, v75, v199
	v_exp_f32_e32 v130, v72
	v_mov_b32_e32 v208, v98
	v_pk_add_f32 v[88:89], v[162:163], v[116:117]
	v_mov_b32_e32 v209, v99
	v_pk_add_f32 v[88:89], v[164:165], v[88:89]
	v_mfma_f32_16x16x32_bf16 v[100:103], v[220:223], v[204:207], v[48:51]
	v_add_f32_e64 v96, v166, v88
	v_add_f32_e64 v97, v167, v89
	v_cvt_pk_bf16_f32 v92, v157, v159
	v_pk_add_f32 v[96:97], v[160:161], v[96:97]
	v_cvt_pk_bf16_f32 v93, v153, v149
	v_pk_add_f32 v[96:97], v[154:155], v[96:97]
	v_cvt_pk_bf16_f32 v94, v151, v133
	v_cvt_pk_bf16_f32 v95, v129, v131
	v_pk_add_f32 v[96:97], v[156:157], v[96:97]
	v_mov_b32_e32 v216, v214
	v_mfma_f32_16x16x32_bf16 v[68:71], v[200:203], v[92:95], v[104:107]
	v_mov_b32_e32 v217, v215
	v_mov_b32_e32 v228, v226
	v_mov_b32_e32 v229, v227
	v_pk_add_f32 v[104:105], v[158:159], v[96:97]
	v_cvt_pk_bf16_f32 v204, v156, v158
	v_cvt_pk_bf16_f32 v205, v152, v148
	v_cvt_pk_bf16_f32 v206, v150, v132
	v_cvt_pk_bf16_f32 v207, v128, v130
	v_pk_add_f32 v[104:105], v[152:153], v[104:105]
	v_mfma_f32_16x16x32_bf16 v[52:55], v[208:211], v[92:95], v[84:87]
	v_mfma_f32_16x16x32_bf16 v[48:51], v[208:211], v[204:207], v[100:103]
	s_nop 2
	v_add_f32_e64 v100, v148, v104
	v_add_f32_e64 v101, v149, v105
	v_mfma_f32_16x16x32_bf16 v[60:63], v[216:219], v[92:95], v[76:79]
	v_add_f32_e64 v100, v150, v100
	v_add_f32_e64 v101, v151, v101
	v_pk_add_f32 v[104:105], v[132:133], v[100:101]
	v_mfma_f32_16x16x32_bf16 v[44:47], v[228:231], v[92:95], v[118:121]
	v_add_f32_e64 v92, v128, v104
	v_add_f32_e64 v93, v129, v105
	v_pk_add_f32 v[92:93], v[130:131], v[92:93]
	v_mfma_f32_16x16x32_bf16 v[64:67], v[200:203], v[204:207], v[112:115]
	v_add_f32_e64 v0, v0, v92
	v_add_f32_e64 v1, v1, v93
	v_mfma_f32_16x16x32_bf16 v[56:59], v[216:219], v[204:207], v[108:111]
	v_mfma_f32_16x16x32_bf16 v[40:43], v[228:231], v[204:207], v[122:125]

; DI f32x4 mfma16(bf16x8 a, bf16x8 b, f32x4 c) { return __builtin_amdgcn_mfma_f32_16x16x32_bf16(a, b, c, 0, 0, 0); }
; __device__ __forceinline__ void attn_item(const AttnItem it, unsigned char* smem) {
;     ...
;     bf16x8 pf[2][NKS];
; #pragma unroll
;     for (int f = 0; f < 2; ++f) {
;       float pv[NKF][4];
;       float ps = 0.f;
; #pragma unroll
;       for (int kf = 0; kf < NKF; ++kf)
; #pragma unroll
;         for (int j = 0; j < 4; ++j) { pv[kf][j] = __builtin_amdgcn_exp2f(s[kf][f][j] - mrun[f]); ps += pv[kf][j]; }
;       lrun[f] += ps;
;       if constexpr (META) {
;         u32x4 w = {pack2(pv[0][0], pv[0][1]), pack2(pv[0][2], pv[0][3]), 0u, 0u};
;         pf[f][0] = __builtin_bit_cast(bf16x8, w);
;       } else {
; #pragma unroll
;         for (int ks = 0; ks < 2; ++ks) {
;           u32x4 w = {pack2(pv[2 * ks][0], pv[2 * ks][1]), pack2(pv[2 * ks][2], pv[2 * ks][3]),
;                      pack2(pv[2 * ks + 1][0], pv[2 * ks + 1][1]), pack2(pv[2 * ks + 1][2], pv[2 * ks + 1][3])};
;           pf[f][ks] = __builtin_bit_cast(bf16x8, w);
;         }
;       }
;     }
; #pragma unroll
;     for (int ks = 0; ks < NKS; ++ks) {
; #pragma unroll
;       for (int d = 0; d < 4; ++d) {
;         const unsigned char* vb = sV + ((d * 2 + ks) << 10) + r * 64;
;         const int x = (r >> 2) << 1;
;         u32x2 lo = *(const u32x2*)(vb + (((q) ^ x) << 3));
;         u32x2 hi = *(const u32x2*)(vb + (((4 + q) ^ x) << 3));
;         u32x4 w = {lo[0], lo[1], hi[0], hi[1]};
;         bf16x8 vf = __builtin_bit_cast(bf16x8, w);
; #pragma unroll
;         for (int f = 0; f < 2; ++f) o[d][f] = mfma16(vf, pf[f][ks], o[d][f]);
;       }
;     }
.LBB0_1560:
	v_sub_f32_e32 v3, v72, v197
	v_sub_f32_e32 v0, v76, v198
	v_exp_f32_e32 v100, v3
	v_sub_f32_e32 v3, v73, v197
	v_exp_f32_e32 v101, v0
	v_sub_f32_e32 v0, v77, v198
	v_exp_f32_e32 v102, v3
	v_add_u32_e32 v3, s12, v171
	v_exp_f32_e32 v103, v0
	v_sub_f32_e32 v0, v78, v198
	v_add_u32_e32 v96, v3, v195
	v_add_u32_e32 v97, v3, v196
	v_exp_f32_e32 v105, v0
	v_sub_f32_e32 v0, v79, v198
	ds_read2st64_b64 v[76:79], v96 offset0:24 offset1:28
	ds_read2st64_b64 v[84:87], v97 offset0:24 offset1:28
	v_sub_f32_e32 v3, v74, v197
	v_exp_f32_e32 v104, v3
	v_sub_f32_e32 v3, v75, v197
	v_exp_f32_e32 v107, v0
	s_waitcnt lgkmcnt(1)
	v_mov_b32_e32 v88, v76
	v_mov_b32_e32 v89, v77
	s_waitcnt lgkmcnt(0)
	v_mov_b32_e32 v90, v84
	v_mov_b32_e32 v91, v85
	v_exp_f32_e32 v106, v3
	v_mov_b32_e32 v84, v78
	v_mov_b32_e32 v85, v79
	v_cvt_pk_bf16_f32 v0, v101, v103
	v_cvt_pk_bf16_f32 v1, v105, v107
	v_mov_b32_e32 v3, v2
	v_cvt_pk_bf16_f32 v92, v100, v102
	v_cvt_pk_bf16_f32 v93, v104, v106
	v_mov_b32_e32 v94, v2
	v_mov_b32_e32 v95, v2
	v_mfma_f32_16x16x32_bf16 v[80:83], v[88:91], v[0:3], v[68:71]
	v_mov_b32_e32 v199, v197
	v_mfma_f32_16x16x32_bf16 v[72:75], v[88:91], v[92:95], v[64:67]
	v_mfma_f32_16x16x32_bf16 v[88:91], v[84:87], v[0:3], v[60:63]
	s_nop 2
	ds_read2st64_b64 v[60:63], v96 offset0:32 offset1:36
	ds_read2st64_b64 v[64:67], v97 offset0:32 offset1:36
	v_mfma_f32_16x16x32_bf16 v[76:79], v[84:87], v[92:95], v[56:59]
	s_waitcnt lgkmcnt(1)
	s_nop 1
	v_mov_b32_e32 v56, v60
	v_mov_b32_e32 v57, v61
	s_waitcnt lgkmcnt(0)
	v_mov_b32_e32 v58, v64
	v_mov_b32_e32 v59, v65
	v_mov_b32_e32 v64, v62
	v_mov_b32_e32 v65, v63
	v_mfma_f32_16x16x32_bf16 v[84:87], v[56:59], v[92:95], v[48:51]
	s_nop 2
	v_add_f32_e64 v48, v100, 0
	v_add_f32_e64 v49, v101, 0
	v_mfma_f32_16x16x32_bf16 v[96:99], v[56:59], v[0:3], v[52:55]
	v_add_f32_e64 v48, v102, v48
	v_add_f32_e64 v49, v103, v49
	v_mfma_f32_16x16x32_bf16 v[100:103], v[64:67], v[0:3], v[44:47]
	v_add_f32_e64 v0, v104, v48
	v_add_f32_e64 v1, v105, v49
	v_mov_b32_e32 v3, v198
	v_pk_add_f32 v[0:1], v[106:107], v[0:1]
	v_mfma_f32_16x16x32_bf16 v[92:95], v[64:67], v[92:95], v[40:43]
	v_add_f32_e64 v0, v146, v0
	v_add_f32_e64 v1, v147, v1
	s_nop 7
	s_nop 1
	v_mov_b64_e32 v[64:65], v[72:73]
	v_mov_b64_e32 v[66:67], v[74:75]
	v_mov_b64_e32 v[56:57], v[76:77]
	v_mov_b64_e32 v[58:59], v[78:79]
	v_mov_b64_e32 v[68:69], v[80:81]
	v_mov_b64_e32 v[70:71], v[82:83]
	v_mov_b64_e32 v[48:49], v[84:85]
	v_mov_b64_e32 v[50:51], v[86:87]
	v_mov_b64_e32 v[60:61], v[88:89]
	v_mov_b64_e32 v[62:63], v[90:91]
	v_mov_b64_e32 v[52:53], v[96:97]
	v_mov_b64_e32 v[54:55], v[98:99]
	v_mov_b64_e32 v[44:45], v[100:101]
	v_mov_b64_e32 v[46:47], v[102:103]
	v_mov_b64_e32 v[40:41], v[92:93]
	v_mov_b64_e32 v[42:43], v[94:95]
	s_andn2_b64 vcc, exec, s[6:7]
	s_add_i32 s11, s11, 1
	s_cbranch_vccnz .LBB0_1566
	s_branch .LBB0_1563

; __device__ __forceinline__ void attn_item(const AttnItem it, unsigned char* smem) {
;     ...
;     if (ti + 1 < nt_all) {
;       unsigned char* nK = smem + ((ti + 1) & 1) * 20480; unsigned char* nV = nK + 12288;
;       *(u32x4*)(nK + kofs[0]) = rk[0];
;       if (k2) *(u32x4*)(nK + kofs[1]) = rk[1];
;       *(u32x4*)(nV + vofs) = rv;
;     }
;     __syncthreads();
;   }
; #pragma unroll
;   for (int f = 0; f < 2; ++f) {
;     float l = lrun[f];
;     l += __shfl_xor(l, 16);
;     l += __shfl_xor(l, 32);
;     const float inv = 1.f / l;
;     const int qr = wave * 32 + f * 16 + r;
;     if (qr < it.nq_valid) {
; #pragma unroll
;       for (int d = 0; d < 4; ++d) {
;         u32x2 v = {pack2(o[d][f][0] * inv, o[d][f][1] * inv), pack2(o[d][f][2] * inv, o[d][f][3] * inv)};
;         *(u32x2*)(it.O + (size_t)qr * 1024 + d * 16 + q * 4) = v;
;       }
;     }
;   }
.LBB0_1563:
	s_bitcmp1_b32 s11, 0
	s_cselect_b32 s6, 0x5000, 0
	v_add_u32_e32 v238, s6, v139
	s_waitcnt vmcnt(2)
	ds_write_b128 v238, v[28:31]
	s_and_saveexec_b64 s[0:1], s[2:3]
	s_cbranch_execz .LBB0_1565
	v_add_u32_e32 v238, s6, v168
	s_waitcnt vmcnt(1)
	ds_write_b128 v238, v[32:35]
.LBB0_1565:
	s_or_b64 exec, exec, s[0:1]
	v_add_u32_e32 v238, s6, v170
	s_waitcnt vmcnt(0)
	ds_write_b128 v238, v[36:39] offset:12288
.LBB0_1566:
	s_mov_b64 s[0:1], 0x80
	v_lshl_add_u64 v[140:141], v[140:141], 0, s[0:1]
	v_lshl_add_u64 v[142:143], v[142:143], 0, s[42:43]
	s_cmp_eq_u32 s10, s11
	v_lshl_add_u64 v[144:145], v[144:145], 0, s[42:43]
	s_waitcnt lgkmcnt(0)
	s_barrier
	s_cbranch_scc0 .LBB0_1550
	v_mov_b64_e32 v[92:93], v[40:41]
	v_mov_b64_e32 v[100:101], v[44:45]
	v_mov_b64_e32 v[84:85], v[48:49]
	v_mov_b64_e32 v[96:97], v[52:53]
	v_mov_b64_e32 v[76:77], v[56:57]
	v_mov_b64_e32 v[88:89], v[60:61]
	v_mov_b64_e32 v[72:73], v[64:65]
	v_mov_b64_e32 v[80:81], v[68:69]
	v_mov_b64_e32 v[94:95], v[42:43]
	v_mov_b64_e32 v[102:103], v[46:47]
	v_mov_b64_e32 v[86:87], v[50:51]
	v_mov_b64_e32 v[98:99], v[54:55]
	v_mov_b64_e32 v[78:79], v[58:59]
	v_mov_b64_e32 v[90:91], v[62:63]
	v_mov_b64_e32 v[74:75], v[66:67]
	v_mov_b64_e32 v[82:83], v[70:71]
	v_cmp_lt_i32_e32 vcc, v175, v176
	s_nop 1
	v_cndmask_b32_e32 v3, v174, v175, vcc
	v_lshlrev_b32_e32 v3, 2, v3
	ds_bpermute_b32 v4, v3, v1
	v_cmp_lt_i32_e32 vcc, v177, v176
	s_waitcnt lgkmcnt(0)
	v_add_f32_e32 v1, v1, v4
	v_cndmask_b32_e32 v5, v174, v177, vcc
	v_lshlrev_b32_e32 v6, 2, v5
	ds_bpermute_b32 v7, v6, v1
	v_lshlrev_b32_e32 v4, 3, v137
	v_mov_b32_e32 v5, v2
	v_lshl_add_u64 v[4:5], s[4:5], 0, v[4:5]
	v_cmp_gt_i32_e32 vcc, s14, v138
	s_and_saveexec_b64 s[0:1], vcc
	s_cbranch_execz .LBB0_1569
	s_waitcnt lgkmcnt(0)
	v_add_f32_e32 v1, v1, v7
	v_div_scale_f32 v7, s[2:3], v1, v1, 1.0
	v_rcp_f32_e32 v8, v7
	v_div_scale_f32 v9, vcc, 1.0, v1, 1.0
	v_ashrrev_i32_e32 v139, 31, v138
	v_fma_f32 v10, -v7, v8, 1.0
	v_fmac_f32_e32 v8, v10, v8
	v_mul_f32_e32 v10, v9, v8
	v_fma_f32 v11, -v7, v10, v9
	v_fmac_f32_e32 v10, v11, v8
	v_fma_f32 v7, -v7, v10, v9
	v_div_fmas_f32 v7, v7, v8, v10
	v_div_fixup_f32 v8, v7, v1, 1.0
	v_lshlrev_b64 v[10:11], 11, v[138:139]
	v_pk_mul_f32 v[12:13], v[80:81], v[8:9] op_sel_hi:[1,0]
	v_pk_mul_f32 v[14:15], v[82:83], v[8:9] op_sel_hi:[1,0]
	v_lshl_add_u64 v[10:11], v[4:5], 0, v[10:11]
	v_cvt_pk_bf16_f32 v12, v12, v13
	v_cvt_pk_bf16_f32 v13, v14, v15
	global_store_dwordx2 v[10:11], v[12:13], off
	v_pk_mul_f32 v[12:13], v[88:89], v[8:9] op_sel_hi:[1,0]
	v_pk_mul_f32 v[14:15], v[90:91], v[8:9] op_sel_hi:[1,0]
	v_cvt_pk_bf16_f32 v12, v12, v13
	v_cvt_pk_bf16_f32 v13, v14, v15
	global_store_dwordx2 v[10:11], v[12:13], off offset:32
	v_pk_mul_f32 v[12:13], v[96:97], v[8:9] op_sel_hi:[1,0]
	v_pk_mul_f32 v[14:15], v[98:99], v[8:9] op_sel_hi:[1,0]
	v_cvt_pk_bf16_f32 v12, v12, v13
	v_cvt_pk_bf16_f32 v13, v14, v15
	global_store_dwordx2 v[10:11], v[12:13], off offset:64
	v_pk_mul_f32 v[12:13], v[100:101], v[8:9] op_sel_hi:[1,0]
	v_pk_mul_f32 v[8:9], v[102:103], v[8:9] op_sel_hi:[1,0]
	v_cvt_pk_bf16_f32 v12, v12, v13
	v_cvt_pk_bf16_f32 v13, v8, v9
	global_store_dwordx2 v[10:11], v[12:13], off offset:96
